# gate GEMM epilogue: row-scale + 16 proj-tile loads hoisted into dead fragment registers with counted vmcnt waits (plus the up-GEMM row-scale prefetch)
# baseline (speedup 1.0000x reference)
; __device__ __forceinline__ unsigned cvt_pk_bf16(float lo, float hi) { unsigned r; asm volatile("v_cvt_pk_bf16_f32 %0, %1, %2" : "=v"(r) : "v"(lo), "v"(hi)); return r; }
; __device__ __forceinline__ float bf_lo(unsigned w) { return __uint_as_float(w << 16); }
; __device__ __forceinline__ float bf_hi(unsigned w) { return __uint_as_float(w & 0xffff0000u); }
; __device__ __forceinline__ float sigmoid_f(float x) { return __builtin_amdgcn_rcpf(1.0f + __builtin_amdgcn_exp2f(-1.4426950408889634f * x)); }
; #define RS ((float*)(WSP() + WS_RS))
;     __device__ __forceinline__ void operator()(const f32x4 (&acc)[2][2][4][2], const Unit& u, int wr, int wc, int fr, int fq) const {
;     ...
;             for (int m = 0; m < 4; ++m) { const size_t off = (size_t)(row0 + ai * HALF + m * 16) * ldc + col0; const float rs = (MODE != 0) ? RS[row0 + ai * HALF + m * 16] : 1.f;
; #pragma unroll
;                 for (int bj = 0; bj < 2; ++bj) { f32x4 v0 = acc[ai][bj][m][0], v1 = acc[ai][bj][m][1];
;                     if (MODE != 0) { v0 = v0 * rs; v1 = v1 * rs; }
;                     if (MODE == 1) {
; #pragma unroll
;                         for (int e = 0; e < 4; ++e) { const float a = fmaxf(v0[e], 0.f), b = fmaxf(v1[e], 0.f); v0[e] = a * a; v1[e] = b * b; } }
;                     if (MODE == 2) { v0 = v0 * sc; v1 = v1 * sc; }
;                     if (MODE == 3) { const u32x4 pw = *(const u32x4*)(P + off + bj * HALF);
;                         v0[0] = bf_lo(pw.x) * sigmoid_f(v0[0]); v0[1] = bf_hi(pw.x) * sigmoid_f(v0[1]); v0[2] = bf_lo(pw.y) * sigmoid_f(v0[2]); v0[3] = bf_hi(pw.y) * sigmoid_f(v0[3]);
;                         v1[0] = bf_lo(pw.z) * sigmoid_f(v1[0]); v1[1] = bf_hi(pw.z) * sigmoid_f(v1[1]); v1[2] = bf_lo(pw.w) * sigmoid_f(v1[2]); v1[3] = bf_hi(pw.w) * sigmoid_f(v1[3]); }
;                     u32x4 w; w.x = cvt_pk_bf16(v0[0], v0[1]); w.y = cvt_pk_bf16(v0[2], v0[3]); w.z = cvt_pk_bf16(v1[0], v1[1]); w.w = cvt_pk_bf16(v1[2], v1[3]);
;                     *(u32x4*)(O + off + bj * HALF) = w; } }
.LBB0_923:
	v_and_b32_e32 v176, 63, v200
	v_and_b32_e32 v177, 0xffffffc0, v147
	v_or_b32_e32 v176, v176, v177
	v_lshl_add_u32 v176, s24, 8, v176
	v_ashrrev_i32_e32 v177, 31, v176
	v_lshl_add_u64 v[176:177], v[176:177], 2, s[12:13]
	global_load_dword v162, v[176:177], off
	global_load_dword v163, v[176:177], off offset:512
	v_lshl_add_u32 v178, s24, 8, v147
	v_lshl_or_b32 v180, s2, 8, v151
	v_ashrrev_i32_e32 v179, 31, v178
	v_ashrrev_i32_e32 v181, 31, v180
	v_lshlrev_b64 v[178:179], 10, v[178:179]
	v_lshl_add_u64 v[178:179], v[178:179], 0, v[180:181]
	v_lshlrev_b64 v[178:179], 1, v[178:179]
	v_lshl_add_u64 v[178:179], s[10:11], 0, v[178:179]
	s_mov_b64 s[98:99], 0x8000
	s_mov_b64 s[100:101], 0x20000
	global_load_dwordx4 v[228:231], v[178:179], off
	global_load_dwordx4 v[232:235], v[178:179], off offset:256
	v_lshl_add_u64 v[178:179], v[178:179], 0, s[98:99]
	global_load_dwordx4 v[236:239], v[178:179], off
	global_load_dwordx4 v[240:243], v[178:179], off offset:256
	v_lshl_add_u64 v[178:179], v[178:179], 0, s[98:99]
	global_load_dwordx4 v[244:247], v[178:179], off
	global_load_dwordx4 v[248:251], v[178:179], off offset:256
	v_lshl_add_u64 v[178:179], v[178:179], 0, s[98:99]
	global_load_dwordx4 v[196:199], v[178:179], off
	global_load_dwordx4 v[184:187], v[178:179], off offset:256
	v_lshl_add_u64 v[178:179], v[178:179], 0, s[98:99]
	v_lshl_add_u64 v[178:179], v[178:179], 0, s[100:101]
	v_and_b32_e32 v164, 15, v200
	v_lshlrev_b32_e32 v164, 2, v164
	v_add_u32_e32 v165, 64, v164
	v_add_u32_e32 v166, 0x80, v164
	v_add_u32_e32 v167, 0xc0, v164
	s_waitcnt vmcnt(8)
	ds_bpermute_b32 v168, v164, v162
	ds_bpermute_b32 v169, v165, v162
	ds_bpermute_b32 v170, v166, v162
	ds_bpermute_b32 v171, v167, v162
	ds_bpermute_b32 v172, v164, v163
	ds_bpermute_b32 v173, v165, v163
	ds_bpermute_b32 v174, v166, v163
	ds_bpermute_b32 v175, v167, v163
	s_waitcnt lgkmcnt(0)
	v_lshl_add_u32 v144, s24, 8, v147
	v_lshl_or_b32 v142, s2, 8, v151
	v_ashrrev_i32_e32 v145, 31, v144
	v_ashrrev_i32_e32 v143, 31, v142
	v_lshlrev_b64 v[140:141], 10, v[144:145]
	v_lshl_add_u64 v[148:149], v[140:141], 0, v[142:143]
	v_lshl_add_u64 v[140:141], v[144:145], 2, s[12:13]
	s_nop 1
	v_mov_b32_e32 v146, v168
	s_mov_b64 s[24:25], 0x40000
	s_andn2_b64 vcc, exec, s[4:5]
	v_pk_mul_f32 v[156:157], v[126:127], v[146:147] op_sel_hi:[1,0]
	v_lshlrev_b64 v[126:127], 1, v[148:149]
	v_pk_mul_f32 v[154:155], v[128:129], v[146:147] op_sel_hi:[1,0]
	v_lshl_add_u64 v[128:129], s[10:11], 0, v[126:127]
	v_pk_mul_f32 v[158:159], v[124:125], v[146:147] op_sel_hi:[1,0]
	v_pk_mul_f32 v[160:161], v[122:123], v[146:147] op_sel_hi:[1,0]
	v_mul_f32_e32 v148, 0xbfb8aa3b, v156
	v_exp_f32_e32 v148, v148
	v_mul_f32_e32 v149, 0xbfb8aa3b, v154
	v_exp_f32_e32 v149, v149
	v_mul_f32_e32 v153, 0xbfb8aa3b, v160
	v_add_f32_e32 v148, 1.0, v148
	v_rcp_f32_e32 v148, v148
	v_add_f32_e32 v149, 1.0, v149
	v_rcp_f32_e32 v149, v149
	v_exp_f32_e32 v153, v153
	v_mul_f32_e32 v154, 0xbfb8aa3b, v158
	v_exp_f32_e32 v154, v154
	v_pk_mul_f32 v[118:119], v[118:119], v[146:147] op_sel_hi:[1,0]
	v_add_f32_e32 v153, 1.0, v153
	v_rcp_f32_e32 v153, v153
	v_add_f32_e32 v154, 1.0, v154
	v_rcp_f32_e32 v154, v154
	v_pk_mul_f32 v[120:121], v[120:121], v[146:147] op_sel_hi:[1,0]
	v_mul_f32_e32 v119, 0xbfb8aa3b, v119
	v_exp_f32_e32 v119, v119
	v_mul_f32_e32 v120, 0xbfb8aa3b, v120
	v_exp_f32_e32 v120, v120
	v_mul_f32_e32 v118, 0xbfb8aa3b, v118
	v_add_f32_e32 v119, 1.0, v119
	v_rcp_f32_e32 v119, v119
	v_add_f32_e32 v120, 1.0, v120
	v_rcp_f32_e32 v120, v120
	v_exp_f32_e32 v118, v118
	s_waitcnt vmcnt(7)
	s_nop 1
	v_mov_b32_e32 v122, v228
	v_mov_b32_e32 v123, v229
	v_mov_b32_e32 v124, v230
	v_mov_b32_e32 v125, v231
	v_lshlrev_b32_e32 v145, 16, v122
	v_mul_f32_e32 v145, v148, v145
	v_mul_f32_e32 v148, 0xbfb8aa3b, v157
	v_exp_f32_e32 v148, v148
	v_and_b32_e32 v122, 0xffff0000, v122
	v_add_f32_e32 v118, 1.0, v118
	v_rcp_f32_e32 v118, v118
	v_add_f32_e32 v148, 1.0, v148
	v_rcp_f32_e32 v148, v148
	s_nop 0
	v_mul_f32_e32 v122, v148, v122
	v_lshlrev_b32_e32 v148, 16, v123
	v_mul_f32_e32 v148, v149, v148
	v_mul_f32_e32 v149, 0xbfb8aa3b, v155
	v_exp_f32_e32 v149, v149
	v_and_b32_e32 v123, 0xffff0000, v123
	v_cvt_pk_bf16_f32 v122, v145, v122
	v_add_f32_e32 v149, 1.0, v149
	v_rcp_f32_e32 v149, v149
	s_nop 0
	v_mul_f32_e32 v123, v149, v123
	v_lshlrev_b32_e32 v149, 16, v124
	v_mul_f32_e32 v149, v153, v149
	v_mul_f32_e32 v153, 0xbfb8aa3b, v161
	v_exp_f32_e32 v153, v153
	v_and_b32_e32 v124, 0xffff0000, v124
	v_cvt_pk_bf16_f32 v123, v148, v123
	v_add_f32_e32 v153, 1.0, v153
	v_rcp_f32_e32 v153, v153
	s_nop 0
	v_mul_f32_e32 v124, v153, v124
	v_lshlrev_b32_e32 v153, 16, v125
	v_mul_f32_e32 v153, v154, v153
	v_mul_f32_e32 v154, 0xbfb8aa3b, v159
	v_exp_f32_e32 v154, v154
	v_and_b32_e32 v125, 0xffff0000, v125
	v_cvt_pk_bf16_f32 v124, v149, v124
	v_lshl_add_u64 v[148:149], s[8:9], 0, v[126:127]
	v_add_f32_e32 v154, 1.0, v154
	v_rcp_f32_e32 v154, v154
	s_nop 0
	v_mul_f32_e32 v125, v154, v125
	v_cvt_pk_bf16_f32 v125, v153, v125
	global_store_dwordx4 v[148:149], v[122:125], off
	s_nop 1
	v_pk_mul_f32 v[122:123], v[116:117], v[146:147] op_sel_hi:[1,0]
	v_pk_mul_f32 v[124:125], v[114:115], v[146:147] op_sel_hi:[1,0]
	v_mul_f32_e32 v122, 0xbfb8aa3b, v122
	v_exp_f32_e32 v122, v122
	s_waitcnt vmcnt(7)
; __device__ __forceinline__ unsigned cvt_pk_bf16(float lo, float hi) { unsigned r; asm volatile("v_cvt_pk_bf16_f32 %0, %1, %2" : "=v"(r) : "v"(lo), "v"(hi)); return r; }
; __device__ __forceinline__ float bf_lo(unsigned w) { return __uint_as_float(w << 16); }
; __device__ __forceinline__ float bf_hi(unsigned w) { return __uint_as_float(w & 0xffff0000u); }
; __device__ __forceinline__ float sigmoid_f(float x) { return __builtin_amdgcn_rcpf(1.0f + __builtin_amdgcn_exp2f(-1.4426950408889634f * x)); }
; #define RS ((float*)(WSP() + WS_RS))
;     __device__ __forceinline__ void operator()(const f32x4 (&acc)[2][2][4][2], const Unit& u, int wr, int wc, int fr, int fq) const {
;     ...
;             for (int m = 0; m < 4; ++m) { const size_t off = (size_t)(row0 + ai * HALF + m * 16) * ldc + col0; const float rs = (MODE != 0) ? RS[row0 + ai * HALF + m * 16] : 1.f;
; #pragma unroll
;                 for (int bj = 0; bj < 2; ++bj) { f32x4 v0 = acc[ai][bj][m][0], v1 = acc[ai][bj][m][1];
;                     if (MODE != 0) { v0 = v0 * rs; v1 = v1 * rs; }
;                     if (MODE == 1) {
; #pragma unroll
;                         for (int e = 0; e < 4; ++e) { const float a = fmaxf(v0[e], 0.f), b = fmaxf(v1[e], 0.f); v0[e] = a * a; v1[e] = b * b; } }
;                     if (MODE == 2) { v0 = v0 * sc; v1 = v1 * sc; }
;                     if (MODE == 3) { const u32x4 pw = *(const u32x4*)(P + off + bj * HALF);
;                         v0[0] = bf_lo(pw.x) * sigmoid_f(v0[0]); v0[1] = bf_hi(pw.x) * sigmoid_f(v0[1]); v0[2] = bf_lo(pw.y) * sigmoid_f(v0[2]); v0[3] = bf_hi(pw.y) * sigmoid_f(v0[3]);
;                         v1[0] = bf_lo(pw.z) * sigmoid_f(v1[0]); v1[1] = bf_hi(pw.z) * sigmoid_f(v1[1]); v1[2] = bf_lo(pw.w) * sigmoid_f(v1[2]); v1[3] = bf_hi(pw.w) * sigmoid_f(v1[3]); }
;                     u32x4 w; w.x = cvt_pk_bf16(v0[0], v0[1]); w.y = cvt_pk_bf16(v0[2], v0[3]); w.z = cvt_pk_bf16(v1[0], v1[1]); w.w = cvt_pk_bf16(v1[2], v1[3]);
;                     *(u32x4*)(O + off + bj * HALF) = w; } }
	s_nop 1
	v_mov_b32_e32 v114, v232
	v_mov_b32_e32 v115, v233
	v_mov_b32_e32 v116, v234
	v_mov_b32_e32 v117, v235
	v_lshlrev_b32_e32 v128, 16, v114
	v_and_b32_e32 v114, 0xffff0000, v114
	v_mul_f32_e32 v114, v119, v114
	v_lshlrev_b32_e32 v119, 16, v115
	v_mul_f32_e32 v119, v120, v119
	v_mul_f32_e32 v120, 0xbfb8aa3b, v121
	v_exp_f32_e32 v120, v120
	v_mul_f32_e32 v121, 0xbfb8aa3b, v124
	v_exp_f32_e32 v121, v121
	v_and_b32_e32 v115, 0xffff0000, v115
	v_add_f32_e32 v120, 1.0, v120
	v_rcp_f32_e32 v120, v120
	v_add_f32_e32 v121, 1.0, v121
	v_rcp_f32_e32 v121, v121
	v_add_f32_e32 v122, 1.0, v122
	v_mul_f32_e32 v115, v120, v115
	v_lshlrev_b32_e32 v120, 16, v116
	v_mul_f32_e32 v120, v121, v120
	v_mul_f32_e32 v121, 0xbfb8aa3b, v125
	v_exp_f32_e32 v121, v121
	v_rcp_f32_e32 v122, v122
	v_and_b32_e32 v116, 0xffff0000, v116
	v_mul_f32_e32 v118, v118, v128
	v_add_f32_e32 v121, 1.0, v121
	v_rcp_f32_e32 v121, v121
	v_cvt_pk_bf16_f32 v114, v118, v114
	v_cvt_pk_bf16_f32 v115, v119, v115
	s_nop 0
	v_mul_f32_e32 v116, v121, v116
	v_lshlrev_b32_e32 v121, 16, v117
	v_mul_f32_e32 v121, v122, v121
	v_mul_f32_e32 v122, 0xbfb8aa3b, v123
	v_exp_f32_e32 v122, v122
	v_and_b32_e32 v117, 0xffff0000, v117
	v_cvt_pk_bf16_f32 v116, v120, v116
	v_add_f32_e32 v122, 1.0, v122
	v_rcp_f32_e32 v122, v122
	s_nop 0
	v_mul_f32_e32 v117, v122, v117
	v_cvt_pk_bf16_f32 v117, v121, v117
	global_store_dwordx4 v[148:149], v[114:117], off offset:256
	s_nop 1
	v_or_b32_e32 v114, 16, v144
	v_ashrrev_i32_e32 v115, 31, v114
	v_lshlrev_b64 v[116:117], 10, v[114:115]
	v_lshl_add_u64 v[114:115], v[114:115], 2, s[12:13]
	s_nop 1
	v_mov_b32_e32 v114, v169
	v_lshl_add_u64 v[116:117], v[116:117], 0, v[142:143]
	v_pk_mul_f32 v[118:119], v[112:113], v[114:115] op_sel_hi:[1,0]
	v_lshlrev_b64 v[112:113], 1, v[116:117]
	v_pk_mul_f32 v[120:121], v[110:111], v[114:115] op_sel_hi:[1,0]
	v_lshl_add_u64 v[110:111], s[10:11], 0, v[112:113]
	v_pk_mul_f32 v[122:123], v[108:109], v[114:115] op_sel_hi:[1,0]
	v_pk_mul_f32 v[124:125], v[106:107], v[114:115] op_sel_hi:[1,0]
	v_mul_f32_e32 v116, 0xbfb8aa3b, v120
	v_exp_f32_e32 v116, v116
	v_mul_f32_e32 v117, 0xbfb8aa3b, v118
	v_exp_f32_e32 v117, v117
	v_mul_f32_e32 v118, 0xbfb8aa3b, v124
	v_add_f32_e32 v116, 1.0, v116
	v_rcp_f32_e32 v116, v116
	v_add_f32_e32 v117, 1.0, v117
	v_rcp_f32_e32 v117, v117
	v_exp_f32_e32 v118, v118
	v_lshl_add_u64 v[112:113], s[8:9], 0, v[112:113]
	v_add_f32_e32 v118, 1.0, v118
	v_rcp_f32_e32 v118, v118
	s_waitcnt vmcnt(7)
	s_nop 1
	v_mov_b32_e32 v106, v236
	v_mov_b32_e32 v107, v237
	v_mov_b32_e32 v108, v238
	v_mov_b32_e32 v109, v239
	v_lshlrev_b32_e32 v115, 16, v106
	v_mul_f32_e32 v115, v116, v115
	v_mul_f32_e32 v116, 0xbfb8aa3b, v121
	v_exp_f32_e32 v116, v116
	v_and_b32_e32 v106, 0xffff0000, v106
	v_pk_mul_f32 v[102:103], v[102:103], v[114:115] op_sel_hi:[1,0]
	v_pk_mul_f32 v[104:105], v[104:105], v[114:115] op_sel_hi:[1,0]
	v_add_f32_e32 v116, 1.0, v116
	v_rcp_f32_e32 v116, v116
	v_mul_f32_e32 v103, 0xbfb8aa3b, v103
	v_exp_f32_e32 v103, v103
	v_mul_f32_e32 v104, 0xbfb8aa3b, v104
	v_mul_f32_e32 v106, v116, v106
	v_lshlrev_b32_e32 v116, 16, v107
	v_mul_f32_e32 v116, v117, v116
	v_mul_f32_e32 v117, 0xbfb8aa3b, v119
	v_exp_f32_e32 v117, v117
	v_and_b32_e32 v107, 0xffff0000, v107
	v_mul_f32_e32 v119, 0xbfb8aa3b, v122
	v_exp_f32_e32 v119, v119
	v_add_f32_e32 v117, 1.0, v117
	v_rcp_f32_e32 v117, v117
	v_cvt_pk_bf16_f32 v106, v115, v106
	v_add_f32_e32 v119, 1.0, v119
	v_rcp_f32_e32 v119, v119
	v_mul_f32_e32 v107, v117, v107
	v_lshlrev_b32_e32 v117, 16, v108
	v_mul_f32_e32 v117, v118, v117
	v_mul_f32_e32 v118, 0xbfb8aa3b, v125
	v_exp_f32_e32 v118, v118
	v_and_b32_e32 v108, 0xffff0000, v108
	v_cvt_pk_bf16_f32 v107, v116, v107
	v_exp_f32_e32 v104, v104
	v_add_f32_e32 v118, 1.0, v118
	v_rcp_f32_e32 v118, v118
	v_add_f32_e32 v103, 1.0, v103
	v_rcp_f32_e32 v103, v103
	v_add_f32_e32 v104, 1.0, v104
	v_mul_f32_e32 v108, v118, v108
	v_lshlrev_b32_e32 v118, 16, v109
	v_mul_f32_e32 v118, v119, v118
	v_mul_f32_e32 v119, 0xbfb8aa3b, v123
	v_exp_f32_e32 v119, v119
	v_and_b32_e32 v109, 0xffff0000, v109
	v_cvt_pk_bf16_f32 v108, v117, v108
	v_rcp_f32_e32 v104, v104
	v_add_f32_e32 v119, 1.0, v119
	v_rcp_f32_e32 v119, v119
	v_mul_f32_e32 v102, 0xbfb8aa3b, v102
	v_exp_f32_e32 v102, v102
	v_mul_f32_e32 v109, v119, v109
	v_cvt_pk_bf16_f32 v109, v118, v109
	global_store_dwordx4 v[112:113], v[106:109], off
	v_add_f32_e32 v102, 1.0, v102
	v_rcp_f32_e32 v102, v102
	v_pk_mul_f32 v[106:107], v[100:101], v[114:115] op_sel_hi:[1,0]
	v_pk_mul_f32 v[108:109], v[98:99], v[114:115] op_sel_hi:[1,0]
	v_mul_f32_e32 v106, 0xbfb8aa3b, v106
	v_exp_f32_e32 v106, v106
	s_waitcnt vmcnt(7)
; __device__ __forceinline__ unsigned cvt_pk_bf16(float lo, float hi) { unsigned r; asm volatile("v_cvt_pk_bf16_f32 %0, %1, %2" : "=v"(r) : "v"(lo), "v"(hi)); return r; }
; __device__ __forceinline__ float bf_lo(unsigned w) { return __uint_as_float(w << 16); }
; __device__ __forceinline__ float bf_hi(unsigned w) { return __uint_as_float(w & 0xffff0000u); }
; __device__ __forceinline__ float sigmoid_f(float x) { return __builtin_amdgcn_rcpf(1.0f + __builtin_amdgcn_exp2f(-1.4426950408889634f * x)); }
; #define RS ((float*)(WSP() + WS_RS))
;     __device__ __forceinline__ void operator()(const f32x4 (&acc)[2][2][4][2], const Unit& u, int wr, int wc, int fr, int fq) const {
;     ...
;             for (int m = 0; m < 4; ++m) { const size_t off = (size_t)(row0 + ai * HALF + m * 16) * ldc + col0; const float rs = (MODE != 0) ? RS[row0 + ai * HALF + m * 16] : 1.f;
; #pragma unroll
;                 for (int bj = 0; bj < 2; ++bj) { f32x4 v0 = acc[ai][bj][m][0], v1 = acc[ai][bj][m][1];
;                     if (MODE != 0) { v0 = v0 * rs; v1 = v1 * rs; }
;                     if (MODE == 1) {
; #pragma unroll
;                         for (int e = 0; e < 4; ++e) { const float a = fmaxf(v0[e], 0.f), b = fmaxf(v1[e], 0.f); v0[e] = a * a; v1[e] = b * b; } }
;                     if (MODE == 2) { v0 = v0 * sc; v1 = v1 * sc; }
;                     if (MODE == 3) { const u32x4 pw = *(const u32x4*)(P + off + bj * HALF);
;                         v0[0] = bf_lo(pw.x) * sigmoid_f(v0[0]); v0[1] = bf_hi(pw.x) * sigmoid_f(v0[1]); v0[2] = bf_lo(pw.y) * sigmoid_f(v0[2]); v0[3] = bf_hi(pw.y) * sigmoid_f(v0[3]);
;                         v1[0] = bf_lo(pw.z) * sigmoid_f(v1[0]); v1[1] = bf_hi(pw.z) * sigmoid_f(v1[1]); v1[2] = bf_lo(pw.w) * sigmoid_f(v1[2]); v1[3] = bf_hi(pw.w) * sigmoid_f(v1[3]); }
;                     u32x4 w; w.x = cvt_pk_bf16(v0[0], v0[1]); w.y = cvt_pk_bf16(v0[2], v0[3]); w.z = cvt_pk_bf16(v1[0], v1[1]); w.w = cvt_pk_bf16(v1[2], v1[3]);
;                     *(u32x4*)(O + off + bj * HALF) = w; } }
	s_nop 1
	v_mov_b32_e32 v98, v240
	v_mov_b32_e32 v99, v241
	v_mov_b32_e32 v100, v242
	v_mov_b32_e32 v101, v243
	v_lshlrev_b32_e32 v110, 16, v98
	v_and_b32_e32 v98, 0xffff0000, v98
	v_mul_f32_e32 v98, v103, v98
	v_lshlrev_b32_e32 v103, 16, v99
	v_mul_f32_e32 v103, v104, v103
	v_mul_f32_e32 v104, 0xbfb8aa3b, v105
	v_exp_f32_e32 v104, v104
	v_mul_f32_e32 v105, 0xbfb8aa3b, v108
	v_exp_f32_e32 v105, v105
	v_and_b32_e32 v99, 0xffff0000, v99
	v_add_f32_e32 v104, 1.0, v104
	v_rcp_f32_e32 v104, v104
	v_add_f32_e32 v105, 1.0, v105
	v_rcp_f32_e32 v105, v105
	v_add_f32_e32 v106, 1.0, v106
	v_mul_f32_e32 v99, v104, v99
	v_lshlrev_b32_e32 v104, 16, v100
	v_mul_f32_e32 v104, v105, v104
	v_mul_f32_e32 v105, 0xbfb8aa3b, v109
	v_exp_f32_e32 v105, v105
	v_rcp_f32_e32 v106, v106
	v_and_b32_e32 v100, 0xffff0000, v100
	v_mul_f32_e32 v102, v102, v110
	v_add_f32_e32 v105, 1.0, v105
	v_rcp_f32_e32 v105, v105
	v_cvt_pk_bf16_f32 v98, v102, v98
	v_cvt_pk_bf16_f32 v99, v103, v99
	s_nop 0
	v_mul_f32_e32 v100, v105, v100
	v_lshlrev_b32_e32 v105, 16, v101
	v_mul_f32_e32 v105, v106, v105
	v_mul_f32_e32 v106, 0xbfb8aa3b, v107
	v_exp_f32_e32 v106, v106
	v_and_b32_e32 v101, 0xffff0000, v101
	v_cvt_pk_bf16_f32 v100, v104, v100
	v_add_f32_e32 v106, 1.0, v106
	v_rcp_f32_e32 v106, v106
	s_nop 0
	v_mul_f32_e32 v101, v106, v101
	v_cvt_pk_bf16_f32 v101, v105, v101
	global_store_dwordx4 v[112:113], v[98:101], off offset:256
	s_nop 1
	v_or_b32_e32 v98, 32, v144
	v_ashrrev_i32_e32 v99, 31, v98
	v_lshlrev_b64 v[100:101], 10, v[98:99]
	v_lshl_add_u64 v[98:99], v[98:99], 2, s[12:13]
	s_nop 1
	v_mov_b32_e32 v98, v170
	v_lshl_add_u64 v[100:101], v[100:101], 0, v[142:143]
	v_pk_mul_f32 v[102:103], v[96:97], v[98:99] op_sel_hi:[1,0]
	v_lshlrev_b64 v[96:97], 1, v[100:101]
	v_pk_mul_f32 v[104:105], v[94:95], v[98:99] op_sel_hi:[1,0]
	v_lshl_add_u64 v[94:95], s[10:11], 0, v[96:97]
	v_pk_mul_f32 v[106:107], v[92:93], v[98:99] op_sel_hi:[1,0]
	v_pk_mul_f32 v[108:109], v[90:91], v[98:99] op_sel_hi:[1,0]
	v_mul_f32_e32 v100, 0xbfb8aa3b, v104
	v_exp_f32_e32 v100, v100
	v_mul_f32_e32 v101, 0xbfb8aa3b, v102
	v_exp_f32_e32 v101, v101
	v_mul_f32_e32 v102, 0xbfb8aa3b, v108
	v_add_f32_e32 v100, 1.0, v100
	v_rcp_f32_e32 v100, v100
	v_add_f32_e32 v101, 1.0, v101
	v_rcp_f32_e32 v101, v101
	v_exp_f32_e32 v102, v102
	v_lshl_add_u64 v[96:97], s[8:9], 0, v[96:97]
	v_add_f32_e32 v102, 1.0, v102
	v_rcp_f32_e32 v102, v102
	s_waitcnt vmcnt(7)
	s_nop 1
	v_mov_b32_e32 v90, v244
	v_mov_b32_e32 v91, v245
	v_mov_b32_e32 v92, v246
	v_mov_b32_e32 v93, v247
	v_lshlrev_b32_e32 v99, 16, v90
	v_mul_f32_e32 v99, v100, v99
	v_mul_f32_e32 v100, 0xbfb8aa3b, v105
	v_exp_f32_e32 v100, v100
	v_and_b32_e32 v90, 0xffff0000, v90
	v_pk_mul_f32 v[86:87], v[86:87], v[98:99] op_sel_hi:[1,0]
	v_pk_mul_f32 v[88:89], v[88:89], v[98:99] op_sel_hi:[1,0]
	v_add_f32_e32 v100, 1.0, v100
	v_rcp_f32_e32 v100, v100
	v_mul_f32_e32 v87, 0xbfb8aa3b, v87
	v_exp_f32_e32 v87, v87
	v_mul_f32_e32 v88, 0xbfb8aa3b, v88
	v_mul_f32_e32 v90, v100, v90
	v_lshlrev_b32_e32 v100, 16, v91
	v_mul_f32_e32 v100, v101, v100
	v_mul_f32_e32 v101, 0xbfb8aa3b, v103
	v_exp_f32_e32 v101, v101
	v_and_b32_e32 v91, 0xffff0000, v91
	v_mul_f32_e32 v103, 0xbfb8aa3b, v106
	v_exp_f32_e32 v103, v103
	v_add_f32_e32 v101, 1.0, v101
	v_rcp_f32_e32 v101, v101
	v_cvt_pk_bf16_f32 v90, v99, v90
	v_add_f32_e32 v103, 1.0, v103
	v_rcp_f32_e32 v103, v103
	v_mul_f32_e32 v91, v101, v91
	v_lshlrev_b32_e32 v101, 16, v92
	v_mul_f32_e32 v101, v102, v101
	v_mul_f32_e32 v102, 0xbfb8aa3b, v109
	v_exp_f32_e32 v102, v102
	v_and_b32_e32 v92, 0xffff0000, v92
	v_cvt_pk_bf16_f32 v91, v100, v91
	v_exp_f32_e32 v88, v88
	v_add_f32_e32 v102, 1.0, v102
	v_rcp_f32_e32 v102, v102
	v_add_f32_e32 v87, 1.0, v87
	v_rcp_f32_e32 v87, v87
	v_add_f32_e32 v88, 1.0, v88
	v_mul_f32_e32 v92, v102, v92
	v_lshlrev_b32_e32 v102, 16, v93
	v_mul_f32_e32 v102, v103, v102
	v_mul_f32_e32 v103, 0xbfb8aa3b, v107
	v_exp_f32_e32 v103, v103
	v_and_b32_e32 v93, 0xffff0000, v93
	v_cvt_pk_bf16_f32 v92, v101, v92
	v_rcp_f32_e32 v88, v88
	v_add_f32_e32 v103, 1.0, v103
	v_rcp_f32_e32 v103, v103
	v_mul_f32_e32 v86, 0xbfb8aa3b, v86
	v_exp_f32_e32 v86, v86
	v_mul_f32_e32 v93, v103, v93
	v_cvt_pk_bf16_f32 v93, v102, v93
	global_store_dwordx4 v[96:97], v[90:93], off
	v_add_f32_e32 v86, 1.0, v86
	v_rcp_f32_e32 v86, v86
	v_pk_mul_f32 v[90:91], v[84:85], v[98:99] op_sel_hi:[1,0]
	v_pk_mul_f32 v[92:93], v[82:83], v[98:99] op_sel_hi:[1,0]
	v_mul_f32_e32 v90, 0xbfb8aa3b, v90
	v_exp_f32_e32 v90, v90
	s_waitcnt vmcnt(7)
	s_nop 1
	v_mov_b32_e32 v82, v248
	v_mov_b32_e32 v83, v249
	v_mov_b32_e32 v84, v250
	v_mov_b32_e32 v85, v251
	v_lshlrev_b32_e32 v94, 16, v82
	v_and_b32_e32 v82, 0xffff0000, v82
	v_mul_f32_e32 v82, v87, v82
	v_lshlrev_b32_e32 v87, 16, v83
	v_mul_f32_e32 v87, v88, v87
	v_mul_f32_e32 v88, 0xbfb8aa3b, v89
	v_exp_f32_e32 v88, v88
	v_mul_f32_e32 v89, 0xbfb8aa3b, v92
	v_exp_f32_e32 v89, v89
	v_and_b32_e32 v83, 0xffff0000, v83
	v_add_f32_e32 v88, 1.0, v88
	v_rcp_f32_e32 v88, v88
	v_add_f32_e32 v89, 1.0, v89
	v_rcp_f32_e32 v89, v89
	v_add_f32_e32 v90, 1.0, v90
	v_mul_f32_e32 v83, v88, v83
	v_lshlrev_b32_e32 v88, 16, v84
	v_mul_f32_e32 v88, v89, v88
	v_mul_f32_e32 v89, 0xbfb8aa3b, v93
	v_exp_f32_e32 v89, v89
	v_rcp_f32_e32 v90, v90
	v_and_b32_e32 v84, 0xffff0000, v84
	v_mul_f32_e32 v86, v86, v94
	v_add_f32_e32 v89, 1.0, v89
	v_rcp_f32_e32 v89, v89
	v_cvt_pk_bf16_f32 v82, v86, v82
	v_cvt_pk_bf16_f32 v83, v87, v83
	s_nop 0
	v_mul_f32_e32 v84, v89, v84
	v_lshlrev_b32_e32 v89, 16, v85
	v_mul_f32_e32 v89, v90, v89
	v_mul_f32_e32 v90, 0xbfb8aa3b, v91
	v_exp_f32_e32 v90, v90
	v_and_b32_e32 v85, 0xffff0000, v85
	v_cvt_pk_bf16_f32 v84, v88, v84
	v_add_f32_e32 v90, 1.0, v90
	v_rcp_f32_e32 v90, v90
	s_nop 0
	v_mul_f32_e32 v85, v90, v85
	v_cvt_pk_bf16_f32 v85, v89, v85
	global_store_dwordx4 v[96:97], v[82:85], off offset:256
	s_nop 1
	v_or_b32_e32 v82, 48, v144
	v_ashrrev_i32_e32 v83, 31, v82
	v_lshlrev_b64 v[84:85], 10, v[82:83]
	v_lshl_add_u64 v[82:83], v[82:83], 2, s[12:13]
	s_nop 1
	v_mov_b32_e32 v82, v171
	v_lshl_add_u64 v[84:85], v[84:85], 0, v[142:143]
	v_pk_mul_f32 v[88:89], v[78:79], v[82:83] op_sel_hi:[1,0]
	v_lshlrev_b64 v[78:79], 1, v[84:85]
	v_pk_mul_f32 v[86:87], v[80:81], v[82:83] op_sel_hi:[1,0]
	v_lshl_add_u64 v[80:81], s[10:11], 0, v[78:79]
	v_pk_mul_f32 v[90:91], v[76:77], v[82:83] op_sel_hi:[1,0]
	v_pk_mul_f32 v[92:93], v[74:75], v[82:83] op_sel_hi:[1,0]
	v_mul_f32_e32 v84, 0xbfb8aa3b, v88
	v_exp_f32_e32 v84, v84
	v_mul_f32_e32 v85, 0xbfb8aa3b, v86
	v_exp_f32_e32 v85, v85
	v_mul_f32_e32 v86, 0xbfb8aa3b, v92
	v_add_f32_e32 v84, 1.0, v84
	v_rcp_f32_e32 v84, v84
	v_add_f32_e32 v85, 1.0, v85
	v_rcp_f32_e32 v85, v85
	v_exp_f32_e32 v86, v86
	v_lshl_add_u64 v[78:79], s[8:9], 0, v[78:79]
	v_add_f32_e32 v86, 1.0, v86
	v_rcp_f32_e32 v86, v86
	s_waitcnt vmcnt(7)
; __device__ __forceinline__ unsigned cvt_pk_bf16(float lo, float hi) { unsigned r; asm volatile("v_cvt_pk_bf16_f32 %0, %1, %2" : "=v"(r) : "v"(lo), "v"(hi)); return r; }
; __device__ __forceinline__ float bf_lo(unsigned w) { return __uint_as_float(w << 16); }
; __device__ __forceinline__ float bf_hi(unsigned w) { return __uint_as_float(w & 0xffff0000u); }
; __device__ __forceinline__ float sigmoid_f(float x) { return __builtin_amdgcn_rcpf(1.0f + __builtin_amdgcn_exp2f(-1.4426950408889634f * x)); }
; #define RS ((float*)(WSP() + WS_RS))
;     __device__ __forceinline__ void operator()(const f32x4 (&acc)[2][2][4][2], const Unit& u, int wr, int wc, int fr, int fq) const {
;     ...
;             for (int m = 0; m < 4; ++m) { const size_t off = (size_t)(row0 + ai * HALF + m * 16) * ldc + col0; const float rs = (MODE != 0) ? RS[row0 + ai * HALF + m * 16] : 1.f;
; #pragma unroll
;                 for (int bj = 0; bj < 2; ++bj) { f32x4 v0 = acc[ai][bj][m][0], v1 = acc[ai][bj][m][1];
;                     if (MODE != 0) { v0 = v0 * rs; v1 = v1 * rs; }
;                     if (MODE == 1) {
; #pragma unroll
;                         for (int e = 0; e < 4; ++e) { const float a = fmaxf(v0[e], 0.f), b = fmaxf(v1[e], 0.f); v0[e] = a * a; v1[e] = b * b; } }
;                     if (MODE == 2) { v0 = v0 * sc; v1 = v1 * sc; }
;                     if (MODE == 3) { const u32x4 pw = *(const u32x4*)(P + off + bj * HALF);
;                         v0[0] = bf_lo(pw.x) * sigmoid_f(v0[0]); v0[1] = bf_hi(pw.x) * sigmoid_f(v0[1]); v0[2] = bf_lo(pw.y) * sigmoid_f(v0[2]); v0[3] = bf_hi(pw.y) * sigmoid_f(v0[3]);
;                         v1[0] = bf_lo(pw.z) * sigmoid_f(v1[0]); v1[1] = bf_hi(pw.z) * sigmoid_f(v1[1]); v1[2] = bf_lo(pw.w) * sigmoid_f(v1[2]); v1[3] = bf_hi(pw.w) * sigmoid_f(v1[3]); }
;                     u32x4 w; w.x = cvt_pk_bf16(v0[0], v0[1]); w.y = cvt_pk_bf16(v0[2], v0[3]); w.z = cvt_pk_bf16(v1[0], v1[1]); w.w = cvt_pk_bf16(v1[2], v1[3]);
;                     *(u32x4*)(O + off + bj * HALF) = w; } }
	s_nop 1
	v_mov_b32_e32 v74, v196
	v_mov_b32_e32 v75, v197
	v_mov_b32_e32 v76, v198
	v_mov_b32_e32 v77, v199
	v_lshlrev_b32_e32 v83, 16, v74
	v_mul_f32_e32 v83, v84, v83
	v_mul_f32_e32 v84, 0xbfb8aa3b, v89
	v_exp_f32_e32 v84, v84
	v_and_b32_e32 v74, 0xffff0000, v74
	v_pk_mul_f32 v[70:71], v[70:71], v[82:83] op_sel_hi:[1,0]
	v_pk_mul_f32 v[72:73], v[72:73], v[82:83] op_sel_hi:[1,0]
	v_add_f32_e32 v84, 1.0, v84
	v_rcp_f32_e32 v84, v84
	v_mul_f32_e32 v71, 0xbfb8aa3b, v71
	v_exp_f32_e32 v71, v71
	v_mul_f32_e32 v72, 0xbfb8aa3b, v72
	v_mul_f32_e32 v74, v84, v74
	v_lshlrev_b32_e32 v84, 16, v75
	v_mul_f32_e32 v84, v85, v84
	v_mul_f32_e32 v85, 0xbfb8aa3b, v87
	v_exp_f32_e32 v85, v85
	v_and_b32_e32 v75, 0xffff0000, v75
	v_mul_f32_e32 v87, 0xbfb8aa3b, v90
	v_exp_f32_e32 v87, v87
	v_add_f32_e32 v85, 1.0, v85
	v_rcp_f32_e32 v85, v85
	v_cvt_pk_bf16_f32 v74, v83, v74
	v_add_f32_e32 v87, 1.0, v87
	v_rcp_f32_e32 v87, v87
	v_mul_f32_e32 v75, v85, v75
	v_lshlrev_b32_e32 v85, 16, v76
	v_mul_f32_e32 v85, v86, v85
	v_mul_f32_e32 v86, 0xbfb8aa3b, v93
	v_exp_f32_e32 v86, v86
	v_and_b32_e32 v76, 0xffff0000, v76
	v_cvt_pk_bf16_f32 v75, v84, v75
	v_exp_f32_e32 v72, v72
	v_add_f32_e32 v86, 1.0, v86
	v_rcp_f32_e32 v86, v86
	v_add_f32_e32 v71, 1.0, v71
	v_rcp_f32_e32 v71, v71
	v_add_f32_e32 v72, 1.0, v72
	v_mul_f32_e32 v76, v86, v76
	v_lshlrev_b32_e32 v86, 16, v77
	v_mul_f32_e32 v86, v87, v86
	v_mul_f32_e32 v87, 0xbfb8aa3b, v91
	v_exp_f32_e32 v87, v87
	v_and_b32_e32 v77, 0xffff0000, v77
	v_cvt_pk_bf16_f32 v76, v85, v76
	v_rcp_f32_e32 v72, v72
	v_add_f32_e32 v87, 1.0, v87
	v_rcp_f32_e32 v87, v87
	v_mul_f32_e32 v70, 0xbfb8aa3b, v70
	v_exp_f32_e32 v70, v70
	v_mul_f32_e32 v77, v87, v77
	v_cvt_pk_bf16_f32 v77, v86, v77
	global_store_dwordx4 v[78:79], v[74:77], off
	v_add_f32_e32 v70, 1.0, v70
	v_rcp_f32_e32 v70, v70
	v_pk_mul_f32 v[74:75], v[68:69], v[82:83] op_sel_hi:[1,0]
	v_pk_mul_f32 v[76:77], v[66:67], v[82:83] op_sel_hi:[1,0]
	v_mul_f32_e32 v74, 0xbfb8aa3b, v74
	v_exp_f32_e32 v74, v74
	s_waitcnt vmcnt(7)
	s_nop 1
	v_mov_b32_e32 v66, v184
	v_mov_b32_e32 v67, v185
	v_mov_b32_e32 v68, v186
	v_mov_b32_e32 v69, v187
	v_lshlrev_b32_e32 v80, 16, v66
	v_and_b32_e32 v66, 0xffff0000, v66
	v_mul_f32_e32 v66, v71, v66
	v_lshlrev_b32_e32 v71, 16, v67
	v_mul_f32_e32 v71, v72, v71
	v_mul_f32_e32 v72, 0xbfb8aa3b, v73
	v_exp_f32_e32 v72, v72
	v_mul_f32_e32 v73, 0xbfb8aa3b, v76
	v_exp_f32_e32 v73, v73
	v_and_b32_e32 v67, 0xffff0000, v67
	v_add_f32_e32 v72, 1.0, v72
	v_rcp_f32_e32 v72, v72
	v_add_f32_e32 v73, 1.0, v73
	v_rcp_f32_e32 v73, v73
	v_add_f32_e32 v74, 1.0, v74
	v_mul_f32_e32 v67, v72, v67
	v_lshlrev_b32_e32 v72, 16, v68
	v_mul_f32_e32 v72, v73, v72
	v_mul_f32_e32 v73, 0xbfb8aa3b, v77
	v_exp_f32_e32 v73, v73
	v_rcp_f32_e32 v74, v74
	v_and_b32_e32 v68, 0xffff0000, v68
	v_mul_f32_e32 v70, v70, v80
	v_add_f32_e32 v73, 1.0, v73
	v_rcp_f32_e32 v73, v73
	v_cvt_pk_bf16_f32 v66, v70, v66
	v_cvt_pk_bf16_f32 v67, v71, v67
	s_nop 0
	v_mul_f32_e32 v68, v73, v68
	v_lshlrev_b32_e32 v73, 16, v69
	v_mul_f32_e32 v73, v74, v73
	v_mul_f32_e32 v74, 0xbfb8aa3b, v75
	v_exp_f32_e32 v74, v74
	v_and_b32_e32 v69, 0xffff0000, v69
	v_cvt_pk_bf16_f32 v68, v72, v68
	v_add_f32_e32 v74, 1.0, v74
	v_rcp_f32_e32 v74, v74
	s_nop 0
	v_mul_f32_e32 v69, v74, v69
	v_cvt_pk_bf16_f32 v69, v73, v69
	global_store_dwordx4 v[78:79], v[66:69], off offset:256
	global_load_dwordx4 v[228:231], v[178:179], off
	global_load_dwordx4 v[232:235], v[178:179], off offset:256
	v_lshl_add_u64 v[178:179], v[178:179], 0, s[98:99]
	global_load_dwordx4 v[236:239], v[178:179], off
	global_load_dwordx4 v[240:243], v[178:179], off offset:256
	v_lshl_add_u64 v[178:179], v[178:179], 0, s[98:99]
	global_load_dwordx4 v[244:247], v[178:179], off
	global_load_dwordx4 v[248:251], v[178:179], off offset:256
	v_lshl_add_u64 v[178:179], v[178:179], 0, s[98:99]
	global_load_dwordx4 v[196:199], v[178:179], off
	global_load_dwordx4 v[184:187], v[178:179], off offset:256
	v_lshl_add_u64 v[178:179], v[178:179], 0, s[98:99]
	s_nop 1
	v_mov_b32_e32 v66, v172
	v_pk_mul_f32 v[70:71], v[62:63], v[66:67] op_sel_hi:[1,0]
	v_lshl_add_u64 v[62:63], v[126:127], 0, s[24:25]
	v_pk_mul_f32 v[68:69], v[64:65], v[66:67] op_sel_hi:[1,0]
	v_lshl_add_u64 v[64:65], s[10:11], 0, v[62:63]
	v_pk_mul_f32 v[72:73], v[60:61], v[66:67] op_sel_hi:[1,0]
	v_pk_mul_f32 v[74:75], v[58:59], v[66:67] op_sel_hi:[1,0]
	v_mul_f32_e32 v70, 0xbfb8aa3b, v70
	v_exp_f32_e32 v70, v70
	v_mul_f32_e32 v68, 0xbfb8aa3b, v68
	v_exp_f32_e32 v68, v68
	v_mul_f32_e32 v69, 0xbfb8aa3b, v69
	v_add_f32_e32 v70, 1.0, v70
	v_rcp_f32_e32 v70, v70
	v_add_f32_e32 v68, 1.0, v68
	v_rcp_f32_e32 v68, v68
	v_exp_f32_e32 v69, v69
	v_lshl_add_u64 v[62:63], s[8:9], 0, v[62:63]
	s_mov_b64 s[24:25], -1
	v_add_f32_e32 v69, 1.0, v69
	v_rcp_f32_e32 v69, v69
	s_waitcnt vmcnt(7)
; __device__ __forceinline__ unsigned cvt_pk_bf16(float lo, float hi) { unsigned r; asm volatile("v_cvt_pk_bf16_f32 %0, %1, %2" : "=v"(r) : "v"(lo), "v"(hi)); return r; }
; __device__ __forceinline__ float bf_lo(unsigned w) { return __uint_as_float(w << 16); }
; __device__ __forceinline__ float bf_hi(unsigned w) { return __uint_as_float(w & 0xffff0000u); }
; __device__ __forceinline__ float sigmoid_f(float x) { return __builtin_amdgcn_rcpf(1.0f + __builtin_amdgcn_exp2f(-1.4426950408889634f * x)); }
; #define RS ((float*)(WSP() + WS_RS))
;     __device__ __forceinline__ void operator()(const f32x4 (&acc)[2][2][4][2], const Unit& u, int wr, int wc, int fr, int fq) const {
;     ...
;             for (int m = 0; m < 4; ++m) { const size_t off = (size_t)(row0 + ai * HALF + m * 16) * ldc + col0; const float rs = (MODE != 0) ? RS[row0 + ai * HALF + m * 16] : 1.f;
; #pragma unroll
;                 for (int bj = 0; bj < 2; ++bj) { f32x4 v0 = acc[ai][bj][m][0], v1 = acc[ai][bj][m][1];
;                     if (MODE != 0) { v0 = v0 * rs; v1 = v1 * rs; }
;                     if (MODE == 1) {
; #pragma unroll
;                         for (int e = 0; e < 4; ++e) { const float a = fmaxf(v0[e], 0.f), b = fmaxf(v1[e], 0.f); v0[e] = a * a; v1[e] = b * b; } }
;                     if (MODE == 2) { v0 = v0 * sc; v1 = v1 * sc; }
;                     if (MODE == 3) { const u32x4 pw = *(const u32x4*)(P + off + bj * HALF);
;                         v0[0] = bf_lo(pw.x) * sigmoid_f(v0[0]); v0[1] = bf_hi(pw.x) * sigmoid_f(v0[1]); v0[2] = bf_lo(pw.y) * sigmoid_f(v0[2]); v0[3] = bf_hi(pw.y) * sigmoid_f(v0[3]);
;                         v1[0] = bf_lo(pw.z) * sigmoid_f(v1[0]); v1[1] = bf_hi(pw.z) * sigmoid_f(v1[1]); v1[2] = bf_lo(pw.w) * sigmoid_f(v1[2]); v1[3] = bf_hi(pw.w) * sigmoid_f(v1[3]); }
;                     u32x4 w; w.x = cvt_pk_bf16(v0[0], v0[1]); w.y = cvt_pk_bf16(v0[2], v0[3]); w.z = cvt_pk_bf16(v1[0], v1[1]); w.w = cvt_pk_bf16(v1[2], v1[3]);
;                     *(u32x4*)(O + off + bj * HALF) = w; } }
	s_nop 1
	v_mov_b32_e32 v58, v228
	v_mov_b32_e32 v59, v229
	v_mov_b32_e32 v60, v230
	v_mov_b32_e32 v61, v231
	v_lshlrev_b32_e32 v67, 16, v58
	v_mul_f32_e32 v67, v70, v67
	v_mul_f32_e32 v70, 0xbfb8aa3b, v71
	v_exp_f32_e32 v70, v70
	v_and_b32_e32 v58, 0xffff0000, v58
	v_mul_f32_e32 v71, 0xbfb8aa3b, v72
	v_exp_f32_e32 v71, v71
	v_add_f32_e32 v70, 1.0, v70
	v_rcp_f32_e32 v70, v70
	v_pk_mul_f32 v[54:55], v[54:55], v[66:67] op_sel_hi:[1,0]
	v_add_f32_e32 v71, 1.0, v71
	v_rcp_f32_e32 v71, v71
	v_mul_f32_e32 v58, v70, v58
	v_lshlrev_b32_e32 v70, 16, v59
	v_mul_f32_e32 v68, v68, v70
	v_mul_f32_e32 v70, 0xbfb8aa3b, v74
	v_exp_f32_e32 v70, v70
	v_and_b32_e32 v59, 0xffff0000, v59
	v_mul_f32_e32 v59, v69, v59
	v_lshlrev_b32_e32 v69, 16, v60
	v_add_f32_e32 v70, 1.0, v70
	v_rcp_f32_e32 v70, v70
	v_and_b32_e32 v60, 0xffff0000, v60
	v_cvt_pk_bf16_f32 v58, v67, v58
	v_cvt_pk_bf16_f32 v59, v68, v59
	v_mul_f32_e32 v69, v70, v69
	v_mul_f32_e32 v70, 0xbfb8aa3b, v75
	v_exp_f32_e32 v70, v70
	v_pk_mul_f32 v[56:57], v[56:57], v[66:67] op_sel_hi:[1,0]
	v_mul_f32_e32 v55, 0xbfb8aa3b, v55
	v_exp_f32_e32 v55, v55
	v_add_f32_e32 v70, 1.0, v70
	v_rcp_f32_e32 v70, v70
	v_mul_f32_e32 v56, 0xbfb8aa3b, v56
	v_exp_f32_e32 v56, v56
	v_add_f32_e32 v55, 1.0, v55
	v_mul_f32_e32 v60, v70, v60
	v_lshlrev_b32_e32 v70, 16, v61
	v_mul_f32_e32 v70, v71, v70
	v_mul_f32_e32 v71, 0xbfb8aa3b, v73
	v_exp_f32_e32 v71, v71
	v_and_b32_e32 v61, 0xffff0000, v61
	v_cvt_pk_bf16_f32 v60, v69, v60
	v_rcp_f32_e32 v55, v55
	v_add_f32_e32 v71, 1.0, v71
	v_rcp_f32_e32 v71, v71
	v_add_f32_e32 v56, 1.0, v56
	v_rcp_f32_e32 v56, v56
	v_mul_f32_e32 v54, 0xbfb8aa3b, v54
	v_mul_f32_e32 v61, v71, v61
	v_cvt_pk_bf16_f32 v61, v70, v61
	global_store_dwordx4 v[62:63], v[58:61], off
	v_exp_f32_e32 v54, v54
	s_nop 0
	v_pk_mul_f32 v[58:59], v[52:53], v[66:67] op_sel_hi:[1,0]
	v_pk_mul_f32 v[60:61], v[50:51], v[66:67] op_sel_hi:[1,0]
	v_mul_f32_e32 v58, 0xbfb8aa3b, v58
	v_exp_f32_e32 v58, v58
	v_add_f32_e32 v54, 1.0, v54
	v_rcp_f32_e32 v54, v54
	v_add_f32_e32 v58, 1.0, v58
	v_rcp_f32_e32 v58, v58
	s_waitcnt vmcnt(7)
	s_nop 1
	v_mov_b32_e32 v50, v232
	v_mov_b32_e32 v51, v233
	v_mov_b32_e32 v52, v234
	v_mov_b32_e32 v53, v235
	v_lshlrev_b32_e32 v64, 16, v50
	v_and_b32_e32 v50, 0xffff0000, v50
	v_mul_f32_e32 v50, v55, v50
	v_lshlrev_b32_e32 v55, 16, v51
	v_mul_f32_e32 v55, v56, v55
	v_mul_f32_e32 v56, 0xbfb8aa3b, v57
	v_exp_f32_e32 v56, v56
	v_mul_f32_e32 v57, 0xbfb8aa3b, v60
	v_exp_f32_e32 v57, v57
	v_and_b32_e32 v51, 0xffff0000, v51
	v_add_f32_e32 v56, 1.0, v56
	v_rcp_f32_e32 v56, v56
	v_add_f32_e32 v57, 1.0, v57
	v_rcp_f32_e32 v57, v57
	v_mul_f32_e32 v54, v54, v64
	v_mul_f32_e32 v51, v56, v51
	v_lshlrev_b32_e32 v56, 16, v52
	v_mul_f32_e32 v56, v57, v56
	v_mul_f32_e32 v57, 0xbfb8aa3b, v61
	v_exp_f32_e32 v57, v57
	v_and_b32_e32 v52, 0xffff0000, v52
	v_cvt_pk_bf16_f32 v50, v54, v50
	v_cvt_pk_bf16_f32 v51, v55, v51
	v_add_f32_e32 v57, 1.0, v57
	v_rcp_f32_e32 v57, v57
	s_nop 0
	v_mul_f32_e32 v52, v57, v52
	v_lshlrev_b32_e32 v57, 16, v53
	v_mul_f32_e32 v57, v58, v57
	v_mul_f32_e32 v58, 0xbfb8aa3b, v59
	v_exp_f32_e32 v58, v58
	v_and_b32_e32 v53, 0xffff0000, v53
	v_cvt_pk_bf16_f32 v52, v56, v52
	v_add_f32_e32 v58, 1.0, v58
	v_rcp_f32_e32 v58, v58
	s_nop 0
	v_mul_f32_e32 v53, v58, v53
	v_cvt_pk_bf16_f32 v53, v57, v53
	global_store_dwordx4 v[62:63], v[50:53], off offset:256
	s_nop 1
	v_mov_b32_e32 v50, v173
	v_pk_mul_f32 v[54:55], v[46:47], v[50:51] op_sel_hi:[1,0]
	v_lshl_add_u64 v[46:47], v[126:127], 0, s[58:59]
	v_pk_mul_f32 v[52:53], v[48:49], v[50:51] op_sel_hi:[1,0]
	v_lshl_add_u64 v[48:49], s[10:11], 0, v[46:47]
	v_pk_mul_f32 v[56:57], v[44:45], v[50:51] op_sel_hi:[1,0]
	v_pk_mul_f32 v[58:59], v[42:43], v[50:51] op_sel_hi:[1,0]
	v_mul_f32_e32 v54, 0xbfb8aa3b, v54
	v_exp_f32_e32 v54, v54
	v_mul_f32_e32 v52, 0xbfb8aa3b, v52
	v_exp_f32_e32 v52, v52
	v_mul_f32_e32 v53, 0xbfb8aa3b, v53
	v_add_f32_e32 v54, 1.0, v54
	v_rcp_f32_e32 v54, v54
	v_add_f32_e32 v52, 1.0, v52
	v_rcp_f32_e32 v52, v52
	v_exp_f32_e32 v53, v53
	v_lshl_add_u64 v[46:47], s[8:9], 0, v[46:47]
	v_add_f32_e32 v53, 1.0, v53
	v_rcp_f32_e32 v53, v53
	s_waitcnt vmcnt(7)
	s_nop 1
	v_mov_b32_e32 v42, v236
	v_mov_b32_e32 v43, v237
	v_mov_b32_e32 v44, v238
	v_mov_b32_e32 v45, v239
	v_lshlrev_b32_e32 v51, 16, v42
	v_mul_f32_e32 v51, v54, v51
	v_mul_f32_e32 v54, 0xbfb8aa3b, v55
	v_exp_f32_e32 v54, v54
	v_and_b32_e32 v42, 0xffff0000, v42
	v_mul_f32_e32 v55, 0xbfb8aa3b, v56
	v_exp_f32_e32 v55, v55
	v_add_f32_e32 v54, 1.0, v54
	v_rcp_f32_e32 v54, v54
	v_pk_mul_f32 v[38:39], v[38:39], v[50:51] op_sel_hi:[1,0]
	v_add_f32_e32 v55, 1.0, v55
	v_rcp_f32_e32 v55, v55
	v_mul_f32_e32 v42, v54, v42
	v_lshlrev_b32_e32 v54, 16, v43
	v_mul_f32_e32 v52, v52, v54
	v_mul_f32_e32 v54, 0xbfb8aa3b, v58
	v_exp_f32_e32 v54, v54
	v_and_b32_e32 v43, 0xffff0000, v43
	v_mul_f32_e32 v43, v53, v43
	v_lshlrev_b32_e32 v53, 16, v44
	v_add_f32_e32 v54, 1.0, v54
	v_rcp_f32_e32 v54, v54
	v_and_b32_e32 v44, 0xffff0000, v44
	v_cvt_pk_bf16_f32 v42, v51, v42
	v_cvt_pk_bf16_f32 v43, v52, v43
	v_mul_f32_e32 v53, v54, v53
	v_mul_f32_e32 v54, 0xbfb8aa3b, v59
	v_exp_f32_e32 v54, v54
	v_pk_mul_f32 v[40:41], v[40:41], v[50:51] op_sel_hi:[1,0]
	v_mul_f32_e32 v39, 0xbfb8aa3b, v39
	v_exp_f32_e32 v39, v39
	v_add_f32_e32 v54, 1.0, v54
	v_rcp_f32_e32 v54, v54
	v_mul_f32_e32 v40, 0xbfb8aa3b, v40
	v_exp_f32_e32 v40, v40
	v_add_f32_e32 v39, 1.0, v39
	v_mul_f32_e32 v44, v54, v44
	v_lshlrev_b32_e32 v54, 16, v45
	v_mul_f32_e32 v54, v55, v54
	v_mul_f32_e32 v55, 0xbfb8aa3b, v57
	v_exp_f32_e32 v55, v55
	v_and_b32_e32 v45, 0xffff0000, v45
	v_cvt_pk_bf16_f32 v44, v53, v44
	v_rcp_f32_e32 v39, v39
	v_add_f32_e32 v55, 1.0, v55
	v_rcp_f32_e32 v55, v55
	v_add_f32_e32 v40, 1.0, v40
	v_rcp_f32_e32 v40, v40
	v_mul_f32_e32 v38, 0xbfb8aa3b, v38
	v_mul_f32_e32 v45, v55, v45
	v_cvt_pk_bf16_f32 v45, v54, v45
	global_store_dwordx4 v[46:47], v[42:45], off
	v_exp_f32_e32 v38, v38
	s_nop 0
	v_pk_mul_f32 v[42:43], v[36:37], v[50:51] op_sel_hi:[1,0]
	v_pk_mul_f32 v[44:45], v[34:35], v[50:51] op_sel_hi:[1,0]
	v_mul_f32_e32 v42, 0xbfb8aa3b, v42
	v_exp_f32_e32 v42, v42
	v_add_f32_e32 v38, 1.0, v38
	v_rcp_f32_e32 v38, v38
	v_add_f32_e32 v42, 1.0, v42
	v_rcp_f32_e32 v42, v42
	s_waitcnt vmcnt(7)
; __device__ __forceinline__ unsigned cvt_pk_bf16(float lo, float hi) { unsigned r; asm volatile("v_cvt_pk_bf16_f32 %0, %1, %2" : "=v"(r) : "v"(lo), "v"(hi)); return r; }
; __device__ __forceinline__ float bf_lo(unsigned w) { return __uint_as_float(w << 16); }
; __device__ __forceinline__ float bf_hi(unsigned w) { return __uint_as_float(w & 0xffff0000u); }
; __device__ __forceinline__ float sigmoid_f(float x) { return __builtin_amdgcn_rcpf(1.0f + __builtin_amdgcn_exp2f(-1.4426950408889634f * x)); }
; #define RS ((float*)(WSP() + WS_RS))
;     __device__ __forceinline__ void operator()(const f32x4 (&acc)[2][2][4][2], const Unit& u, int wr, int wc, int fr, int fq) const {
;     ...
;             for (int m = 0; m < 4; ++m) { const size_t off = (size_t)(row0 + ai * HALF + m * 16) * ldc + col0; const float rs = (MODE != 0) ? RS[row0 + ai * HALF + m * 16] : 1.f;
; #pragma unroll
;                 for (int bj = 0; bj < 2; ++bj) { f32x4 v0 = acc[ai][bj][m][0], v1 = acc[ai][bj][m][1];
;                     if (MODE != 0) { v0 = v0 * rs; v1 = v1 * rs; }
;                     if (MODE == 1) {
; #pragma unroll
;                         for (int e = 0; e < 4; ++e) { const float a = fmaxf(v0[e], 0.f), b = fmaxf(v1[e], 0.f); v0[e] = a * a; v1[e] = b * b; } }
;                     if (MODE == 2) { v0 = v0 * sc; v1 = v1 * sc; }
;                     if (MODE == 3) { const u32x4 pw = *(const u32x4*)(P + off + bj * HALF);
;                         v0[0] = bf_lo(pw.x) * sigmoid_f(v0[0]); v0[1] = bf_hi(pw.x) * sigmoid_f(v0[1]); v0[2] = bf_lo(pw.y) * sigmoid_f(v0[2]); v0[3] = bf_hi(pw.y) * sigmoid_f(v0[3]);
;                         v1[0] = bf_lo(pw.z) * sigmoid_f(v1[0]); v1[1] = bf_hi(pw.z) * sigmoid_f(v1[1]); v1[2] = bf_lo(pw.w) * sigmoid_f(v1[2]); v1[3] = bf_hi(pw.w) * sigmoid_f(v1[3]); }
;                     u32x4 w; w.x = cvt_pk_bf16(v0[0], v0[1]); w.y = cvt_pk_bf16(v0[2], v0[3]); w.z = cvt_pk_bf16(v1[0], v1[1]); w.w = cvt_pk_bf16(v1[2], v1[3]);
;                     *(u32x4*)(O + off + bj * HALF) = w; } }
	s_nop 1
	v_mov_b32_e32 v34, v240
	v_mov_b32_e32 v35, v241
	v_mov_b32_e32 v36, v242
	v_mov_b32_e32 v37, v243
	v_lshlrev_b32_e32 v48, 16, v34
	v_and_b32_e32 v34, 0xffff0000, v34
	v_mul_f32_e32 v34, v39, v34
	v_lshlrev_b32_e32 v39, 16, v35
	v_mul_f32_e32 v39, v40, v39
	v_mul_f32_e32 v40, 0xbfb8aa3b, v41
	v_exp_f32_e32 v40, v40
	v_mul_f32_e32 v41, 0xbfb8aa3b, v44
	v_exp_f32_e32 v41, v41
	v_and_b32_e32 v35, 0xffff0000, v35
	v_add_f32_e32 v40, 1.0, v40
	v_rcp_f32_e32 v40, v40
	v_add_f32_e32 v41, 1.0, v41
	v_rcp_f32_e32 v41, v41
	v_mul_f32_e32 v38, v38, v48
	v_mul_f32_e32 v35, v40, v35
	v_lshlrev_b32_e32 v40, 16, v36
	v_mul_f32_e32 v40, v41, v40
	v_mul_f32_e32 v41, 0xbfb8aa3b, v45
	v_exp_f32_e32 v41, v41
	v_and_b32_e32 v36, 0xffff0000, v36
	v_cvt_pk_bf16_f32 v34, v38, v34
	v_cvt_pk_bf16_f32 v35, v39, v35
	v_add_f32_e32 v41, 1.0, v41
	v_rcp_f32_e32 v41, v41
	s_nop 0
	v_mul_f32_e32 v36, v41, v36
	v_lshlrev_b32_e32 v41, 16, v37
	v_mul_f32_e32 v41, v42, v41
	v_mul_f32_e32 v42, 0xbfb8aa3b, v43
	v_exp_f32_e32 v42, v42
	v_and_b32_e32 v37, 0xffff0000, v37
	v_cvt_pk_bf16_f32 v36, v40, v36
	v_add_f32_e32 v42, 1.0, v42
	v_rcp_f32_e32 v42, v42
	s_nop 0
	v_mul_f32_e32 v37, v42, v37
	v_cvt_pk_bf16_f32 v37, v41, v37
	global_store_dwordx4 v[46:47], v[34:37], off offset:256
	s_nop 1
	v_mov_b32_e32 v34, v174
	v_pk_mul_f32 v[38:39], v[30:31], v[34:35] op_sel_hi:[1,0]
	v_lshl_add_u64 v[30:31], v[126:127], 0, s[66:67]
	v_pk_mul_f32 v[36:37], v[32:33], v[34:35] op_sel_hi:[1,0]
	v_lshl_add_u64 v[32:33], s[10:11], 0, v[30:31]
	v_pk_mul_f32 v[40:41], v[28:29], v[34:35] op_sel_hi:[1,0]
	v_pk_mul_f32 v[42:43], v[26:27], v[34:35] op_sel_hi:[1,0]
	v_mul_f32_e32 v38, 0xbfb8aa3b, v38
	v_exp_f32_e32 v38, v38
	v_mul_f32_e32 v36, 0xbfb8aa3b, v36
	v_exp_f32_e32 v36, v36
	v_mul_f32_e32 v37, 0xbfb8aa3b, v37
	v_add_f32_e32 v38, 1.0, v38
	v_rcp_f32_e32 v38, v38
	v_add_f32_e32 v36, 1.0, v36
	v_rcp_f32_e32 v36, v36
	v_exp_f32_e32 v37, v37
	v_lshl_add_u64 v[30:31], s[8:9], 0, v[30:31]
	v_add_f32_e32 v37, 1.0, v37
	v_rcp_f32_e32 v37, v37
	s_waitcnt vmcnt(7)
	s_nop 1
	v_mov_b32_e32 v26, v244
	v_mov_b32_e32 v27, v245
	v_mov_b32_e32 v28, v246
	v_mov_b32_e32 v29, v247
	v_lshlrev_b32_e32 v35, 16, v26
	v_mul_f32_e32 v35, v38, v35
	v_mul_f32_e32 v38, 0xbfb8aa3b, v39
	v_exp_f32_e32 v38, v38
	v_and_b32_e32 v26, 0xffff0000, v26
	v_mul_f32_e32 v39, 0xbfb8aa3b, v40
	v_exp_f32_e32 v39, v39
	v_add_f32_e32 v38, 1.0, v38
	v_rcp_f32_e32 v38, v38
	v_pk_mul_f32 v[22:23], v[22:23], v[34:35] op_sel_hi:[1,0]
	v_add_f32_e32 v39, 1.0, v39
	v_rcp_f32_e32 v39, v39
	v_mul_f32_e32 v26, v38, v26
	v_lshlrev_b32_e32 v38, 16, v27
	v_mul_f32_e32 v36, v36, v38
	v_mul_f32_e32 v38, 0xbfb8aa3b, v42
	v_exp_f32_e32 v38, v38
	v_and_b32_e32 v27, 0xffff0000, v27
	v_mul_f32_e32 v27, v37, v27
	v_lshlrev_b32_e32 v37, 16, v28
	v_add_f32_e32 v38, 1.0, v38
	v_rcp_f32_e32 v38, v38
	v_and_b32_e32 v28, 0xffff0000, v28
	v_cvt_pk_bf16_f32 v26, v35, v26
	v_cvt_pk_bf16_f32 v27, v36, v27
	v_mul_f32_e32 v37, v38, v37
	v_mul_f32_e32 v38, 0xbfb8aa3b, v43
	v_exp_f32_e32 v38, v38
	v_pk_mul_f32 v[24:25], v[24:25], v[34:35] op_sel_hi:[1,0]
	v_mul_f32_e32 v23, 0xbfb8aa3b, v23
	v_exp_f32_e32 v23, v23
	v_add_f32_e32 v38, 1.0, v38
	v_rcp_f32_e32 v38, v38
	v_mul_f32_e32 v24, 0xbfb8aa3b, v24
	v_exp_f32_e32 v24, v24
	v_add_f32_e32 v23, 1.0, v23
	v_mul_f32_e32 v28, v38, v28
	v_lshlrev_b32_e32 v38, 16, v29
	v_mul_f32_e32 v38, v39, v38
	v_mul_f32_e32 v39, 0xbfb8aa3b, v41
	v_exp_f32_e32 v39, v39
	v_and_b32_e32 v29, 0xffff0000, v29
	v_cvt_pk_bf16_f32 v28, v37, v28
	v_rcp_f32_e32 v23, v23
	v_add_f32_e32 v39, 1.0, v39
	v_rcp_f32_e32 v39, v39
	v_add_f32_e32 v24, 1.0, v24
	v_rcp_f32_e32 v24, v24
	v_mul_f32_e32 v22, 0xbfb8aa3b, v22
	v_mul_f32_e32 v29, v39, v29
	v_cvt_pk_bf16_f32 v29, v38, v29
	global_store_dwordx4 v[30:31], v[26:29], off
	v_exp_f32_e32 v22, v22
	s_nop 0
	v_pk_mul_f32 v[26:27], v[20:21], v[34:35] op_sel_hi:[1,0]
	v_pk_mul_f32 v[28:29], v[18:19], v[34:35] op_sel_hi:[1,0]
	v_mul_f32_e32 v26, 0xbfb8aa3b, v26
	v_exp_f32_e32 v26, v26
	v_add_f32_e32 v22, 1.0, v22
	v_rcp_f32_e32 v22, v22
	v_add_f32_e32 v26, 1.0, v26
	v_rcp_f32_e32 v26, v26
	s_waitcnt vmcnt(7)
; __device__ __forceinline__ unsigned cvt_pk_bf16(float lo, float hi) { unsigned r; asm volatile("v_cvt_pk_bf16_f32 %0, %1, %2" : "=v"(r) : "v"(lo), "v"(hi)); return r; }
;     __device__ __forceinline__ void operator()(const f32x4 (&acc)[2][2][4][2], const Unit& u, int wr, int wc, int fr, int fq) const {
;     ...
;             for (int m = 0; m < 4; ++m) { const size_t off = (size_t)(row0 + ai * HALF + m * 16) * ldc + col0; const float rs = (MODE != 0) ? RS[row0 + ai * HALF + m * 16] : 1.f;
; #pragma unroll
;                 for (int bj = 0; bj < 2; ++bj) { f32x4 v0 = acc[ai][bj][m][0], v1 = acc[ai][bj][m][1];
;                     if (MODE != 0) { v0 = v0 * rs; v1 = v1 * rs; }
;                     if (MODE == 1) {
; #pragma unroll
;                         for (int e = 0; e < 4; ++e) { const float a = fmaxf(v0[e], 0.f), b = fmaxf(v1[e], 0.f); v0[e] = a * a; v1[e] = b * b; } }
;                     if (MODE == 2) { v0 = v0 * sc; v1 = v1 * sc; }
;                     if (MODE == 3) { const u32x4 pw = *(const u32x4*)(P + off + bj * HALF);
;                         v0[0] = bf_lo(pw.x) * sigmoid_f(v0[0]); v0[1] = bf_hi(pw.x) * sigmoid_f(v0[1]); v0[2] = bf_lo(pw.y) * sigmoid_f(v0[2]); v0[3] = bf_hi(pw.y) * sigmoid_f(v0[3]);
;                         v1[0] = bf_lo(pw.z) * sigmoid_f(v1[0]); v1[1] = bf_hi(pw.z) * sigmoid_f(v1[1]); v1[2] = bf_lo(pw.w) * sigmoid_f(v1[2]); v1[3] = bf_hi(pw.w) * sigmoid_f(v1[3]); }
;                     u32x4 w; w.x = cvt_pk_bf16(v0[0], v0[1]); w.y = cvt_pk_bf16(v0[2], v0[3]); w.z = cvt_pk_bf16(v1[0], v1[1]); w.w = cvt_pk_bf16(v1[2], v1[3]);
;                     *(u32x4*)(O + off + bj * HALF) = w; } }
; template <class Epi, class Sched, bool ALIGN_EPI = false, bool SP2 = false>
; __device__ __forceinline__ void gemm_phase(PG8_LAS unsigned char* lds, const Gemm g, const Sched& S, const Epi& E, int tid_in) {
;     ...
;         if (!has_next) break;
; #pragma unroll
;         for (int a = 0; a < 2; ++a)
; #pragma unroll
;             for (int b = 0; b < 2; ++b)
; #pragma unroll
;                 for (int m = 0; m < 4; ++m)
; #pragma unroll
;                     for (int n = 0; n < 2; ++n) acc[a][b][m][n] = (f32x4){0.f, 0.f, 0.f, 0.f};
;         cur = nxt; cA = nA; cB = nB; ++ui;
;         if constexpr (ALIGN_EPI) { if (wr == 1) PG8_BAR; }
;     }
;     PG8_WAIT_V(0);
;     if constexpr (!ALIGN_EPI) { if (wr == 0) PG8_BAR; }
;     PG8_BAR;
	s_nop 1
	v_mov_b32_e32 v18, v248
	v_mov_b32_e32 v19, v249
	v_mov_b32_e32 v20, v250
	v_mov_b32_e32 v21, v251
	v_lshlrev_b32_e32 v32, 16, v18
	v_and_b32_e32 v18, 0xffff0000, v18
	v_mul_f32_e32 v18, v23, v18
	v_lshlrev_b32_e32 v23, 16, v19
	v_mul_f32_e32 v23, v24, v23
	v_mul_f32_e32 v24, 0xbfb8aa3b, v25
	v_exp_f32_e32 v24, v24
	v_mul_f32_e32 v25, 0xbfb8aa3b, v28
	v_exp_f32_e32 v25, v25
	v_and_b32_e32 v19, 0xffff0000, v19
	v_add_f32_e32 v24, 1.0, v24
	v_rcp_f32_e32 v24, v24
	v_add_f32_e32 v25, 1.0, v25
	v_rcp_f32_e32 v25, v25
	v_mul_f32_e32 v22, v22, v32
	v_mul_f32_e32 v19, v24, v19
	v_lshlrev_b32_e32 v24, 16, v20
	v_mul_f32_e32 v24, v25, v24
	v_mul_f32_e32 v25, 0xbfb8aa3b, v29
	v_exp_f32_e32 v25, v25
	v_and_b32_e32 v20, 0xffff0000, v20
	v_cvt_pk_bf16_f32 v18, v22, v18
	v_cvt_pk_bf16_f32 v19, v23, v19
	v_add_f32_e32 v25, 1.0, v25
	v_rcp_f32_e32 v25, v25
	s_nop 0
	v_mul_f32_e32 v20, v25, v20
	v_lshlrev_b32_e32 v25, 16, v21
	v_mul_f32_e32 v25, v26, v25
	v_mul_f32_e32 v26, 0xbfb8aa3b, v27
	v_exp_f32_e32 v26, v26
	v_and_b32_e32 v21, 0xffff0000, v21
	v_cvt_pk_bf16_f32 v20, v24, v20
	v_add_f32_e32 v26, 1.0, v26
	v_rcp_f32_e32 v26, v26
	s_nop 0
	v_mul_f32_e32 v21, v26, v21
	v_cvt_pk_bf16_f32 v21, v25, v21
	global_store_dwordx4 v[30:31], v[18:21], off offset:256
	s_nop 1
	v_mov_b32_e32 v18, v175
	v_pk_mul_f32 v[22:23], v[14:15], v[18:19] op_sel_hi:[1,0]
	v_pk_mul_f32 v[20:21], v[16:17], v[18:19] op_sel_hi:[1,0]
	v_lshl_add_u64 v[16:17], v[126:127], 0, s[68:69]
	v_lshl_add_u64 v[14:15], s[10:11], 0, v[16:17]
	v_pk_mul_f32 v[24:25], v[12:13], v[18:19] op_sel_hi:[1,0]
	v_pk_mul_f32 v[26:27], v[10:11], v[18:19] op_sel_hi:[1,0]
	v_mul_f32_e32 v22, 0xbfb8aa3b, v22
	v_exp_f32_e32 v22, v22
	v_mul_f32_e32 v20, 0xbfb8aa3b, v20
	v_exp_f32_e32 v20, v20
	v_mul_f32_e32 v21, 0xbfb8aa3b, v21
	v_add_f32_e32 v22, 1.0, v22
	v_rcp_f32_e32 v22, v22
	v_add_f32_e32 v20, 1.0, v20
	v_rcp_f32_e32 v20, v20
	v_exp_f32_e32 v21, v21
	v_lshl_add_u64 v[16:17], s[8:9], 0, v[16:17]
	v_add_f32_e32 v21, 1.0, v21
	v_rcp_f32_e32 v21, v21
	s_waitcnt vmcnt(7)
	s_nop 1
	v_mov_b32_e32 v10, v196
	v_mov_b32_e32 v11, v197
	v_mov_b32_e32 v12, v198
	v_mov_b32_e32 v13, v199
	v_lshlrev_b32_e32 v19, 16, v10
	v_mul_f32_e32 v19, v22, v19
	v_mul_f32_e32 v22, 0xbfb8aa3b, v23
	v_exp_f32_e32 v22, v22
	v_and_b32_e32 v10, 0xffff0000, v10
	v_mul_f32_e32 v23, 0xbfb8aa3b, v24
	v_exp_f32_e32 v23, v23
	v_add_f32_e32 v22, 1.0, v22
	v_rcp_f32_e32 v22, v22
	v_pk_mul_f32 v[6:7], v[6:7], v[18:19] op_sel_hi:[1,0]
	v_add_f32_e32 v23, 1.0, v23
	v_rcp_f32_e32 v23, v23
	v_mul_f32_e32 v10, v22, v10
	v_lshlrev_b32_e32 v22, 16, v11
	v_mul_f32_e32 v20, v20, v22
	v_mul_f32_e32 v22, 0xbfb8aa3b, v26
	v_exp_f32_e32 v22, v22
	v_and_b32_e32 v11, 0xffff0000, v11
	v_mul_f32_e32 v11, v21, v11
	v_lshlrev_b32_e32 v21, 16, v12
	v_add_f32_e32 v22, 1.0, v22
	v_rcp_f32_e32 v22, v22
	v_and_b32_e32 v12, 0xffff0000, v12
	v_cvt_pk_bf16_f32 v10, v19, v10
	v_cvt_pk_bf16_f32 v11, v20, v11
	v_mul_f32_e32 v21, v22, v21
	v_mul_f32_e32 v22, 0xbfb8aa3b, v27
	v_exp_f32_e32 v22, v22
	v_pk_mul_f32 v[8:9], v[8:9], v[18:19] op_sel_hi:[1,0]
	v_mul_f32_e32 v7, 0xbfb8aa3b, v7
	v_exp_f32_e32 v7, v7
	v_add_f32_e32 v22, 1.0, v22
	v_rcp_f32_e32 v22, v22
	v_mul_f32_e32 v8, 0xbfb8aa3b, v8
	v_exp_f32_e32 v8, v8
	v_add_f32_e32 v7, 1.0, v7
	v_mul_f32_e32 v12, v22, v12
	v_lshlrev_b32_e32 v22, 16, v13
	v_mul_f32_e32 v22, v23, v22
	v_mul_f32_e32 v23, 0xbfb8aa3b, v25
	v_exp_f32_e32 v23, v23
	v_and_b32_e32 v13, 0xffff0000, v13
	v_cvt_pk_bf16_f32 v12, v21, v12
	v_rcp_f32_e32 v7, v7
	v_add_f32_e32 v23, 1.0, v23
	v_rcp_f32_e32 v23, v23
	v_add_f32_e32 v8, 1.0, v8
	v_rcp_f32_e32 v8, v8
	v_mul_f32_e32 v6, 0xbfb8aa3b, v6
	v_mul_f32_e32 v13, v23, v13
	v_cvt_pk_bf16_f32 v13, v22, v13
	global_store_dwordx4 v[16:17], v[10:13], off
	v_exp_f32_e32 v6, v6
	s_nop 0
	v_pk_mul_f32 v[10:11], v[4:5], v[18:19] op_sel_hi:[1,0]
	v_pk_mul_f32 v[12:13], v[2:3], v[18:19] op_sel_hi:[1,0]
	v_mul_f32_e32 v10, 0xbfb8aa3b, v10
	v_exp_f32_e32 v10, v10
	v_add_f32_e32 v6, 1.0, v6
	v_rcp_f32_e32 v6, v6
	v_add_f32_e32 v10, 1.0, v10
	v_rcp_f32_e32 v10, v10
	s_waitcnt vmcnt(7)
	s_nop 1
	v_mov_b32_e32 v2, v184
	v_mov_b32_e32 v3, v185
	v_mov_b32_e32 v4, v186
	v_mov_b32_e32 v5, v187
	v_lshlrev_b32_e32 v14, 16, v2
	v_and_b32_e32 v2, 0xffff0000, v2
	v_mul_f32_e32 v2, v7, v2
	v_lshlrev_b32_e32 v7, 16, v3
	v_mul_f32_e32 v7, v8, v7
	v_mul_f32_e32 v8, 0xbfb8aa3b, v9
	v_exp_f32_e32 v8, v8
	v_mul_f32_e32 v9, 0xbfb8aa3b, v12
	v_exp_f32_e32 v9, v9
	v_and_b32_e32 v3, 0xffff0000, v3
	v_add_f32_e32 v8, 1.0, v8
	v_rcp_f32_e32 v8, v8
	v_add_f32_e32 v9, 1.0, v9
	v_rcp_f32_e32 v9, v9
	v_mul_f32_e32 v6, v6, v14
	v_mul_f32_e32 v3, v8, v3
	v_lshlrev_b32_e32 v8, 16, v4
	v_mul_f32_e32 v8, v9, v8
	v_mul_f32_e32 v9, 0xbfb8aa3b, v13
	v_exp_f32_e32 v9, v9
	v_and_b32_e32 v4, 0xffff0000, v4
	v_cvt_pk_bf16_f32 v2, v6, v2
	v_cvt_pk_bf16_f32 v3, v7, v3
	v_add_f32_e32 v9, 1.0, v9
	v_rcp_f32_e32 v9, v9
	s_nop 0
	v_mul_f32_e32 v4, v9, v4
	v_lshlrev_b32_e32 v9, 16, v5
	v_mul_f32_e32 v9, v10, v9
	v_mul_f32_e32 v10, 0xbfb8aa3b, v11
	v_exp_f32_e32 v10, v10
	v_and_b32_e32 v5, 0xffff0000, v5
	v_cvt_pk_bf16_f32 v4, v8, v4
	v_add_f32_e32 v10, 1.0, v10
	v_rcp_f32_e32 v10, v10
	s_nop 0
	v_mul_f32_e32 v5, v10, v5
	v_cvt_pk_bf16_f32 v5, v9, v5
	global_store_dwordx4 v[16:17], v[2:5], off offset:256
	s_cbranch_vccnz .LBB0_912
	s_andn2_b64 vcc, exec, s[6:7]
	s_cbranch_vccnz .LBB0_911
	s_barrier
	s_branch .LBB0_911

; __global__ void __launch_bounds__(NWAVES * 64, 2) mk_fwd(Args args) {
	.amdhsa_kernel _Z6mk_fwd4Args
		.amdhsa_group_segment_fixed_size 0
		.amdhsa_private_segment_fixed_size 0
		.amdhsa_kernarg_size 456
		.amdhsa_user_sgpr_count 2
		.amdhsa_user_sgpr_dispatch_ptr 0
		.amdhsa_user_sgpr_queue_ptr 0
		.amdhsa_user_sgpr_kernarg_segment_ptr 1
		.amdhsa_user_sgpr_dispatch_id 0
		.amdhsa_user_sgpr_kernarg_preload_length 0
		.amdhsa_user_sgpr_kernarg_preload_offset 0
		.amdhsa_user_sgpr_private_segment_size 0
		.amdhsa_uses_dynamic_stack 0
		.amdhsa_enable_private_segment 0
		.amdhsa_system_sgpr_workgroup_id_x 1
		.amdhsa_system_sgpr_workgroup_id_y 0
		.amdhsa_system_sgpr_workgroup_id_z 0
		.amdhsa_system_sgpr_workgroup_info 0
		.amdhsa_system_vgpr_workitem_id 2
		.amdhsa_next_free_vgpr 256
		.amdhsa_next_free_sgpr 102
		.amdhsa_accum_offset 256
		.amdhsa_reserve_vcc 1
		.amdhsa_float_round_mode_32 0
		.amdhsa_float_round_mode_16_64 0
		.amdhsa_float_denorm_mode_32 3
		.amdhsa_float_denorm_mode_16_64 3
		.amdhsa_dx10_clamp 1
		.amdhsa_ieee_mode 1
		.amdhsa_fp16_overflow 0
		.amdhsa_tg_split 0
		.amdhsa_exception_fp_ieee_invalid_op 0
		.amdhsa_exception_fp_denorm_src 0
		.amdhsa_exception_fp_ieee_div_zero 0
		.amdhsa_exception_fp_ieee_overflow 0
		.amdhsa_exception_fp_ieee_underflow 0
		.amdhsa_exception_fp_ieee_inexact 0
		.amdhsa_exception_int_div_zero 0
	.end_amdhsa_kernel

; __global__ void __launch_bounds__(NWAVES * 64, 2) mk_fwd(Args args) {
amdhsa.kernels:
  - .agpr_count:     0
    .args:
      - .offset:         0
        .size:           200
        .value_kind:     by_value
      - .offset:         200
        .size:           4
        .value_kind:     hidden_block_count_x
      - .offset:         204
        .size:           4
        .value_kind:     hidden_block_count_y
      - .offset:         208
        .size:           4
        .value_kind:     hidden_block_count_z
      - .offset:         212
        .size:           2
        .value_kind:     hidden_group_size_x
      - .offset:         214
        .size:           2
        .value_kind:     hidden_group_size_y
      - .offset:         216
        .size:           2
        .value_kind:     hidden_group_size_z
      - .offset:         218
        .size:           2
        .value_kind:     hidden_remainder_x
      - .offset:         220
        .size:           2
        .value_kind:     hidden_remainder_y
      - .offset:         222
        .size:           2
        .value_kind:     hidden_remainder_z
      - .offset:         240
        .size:           8
        .value_kind:     hidden_global_offset_x
      - .offset:         248
        .size:           8
        .value_kind:     hidden_global_offset_y
      - .offset:         256
        .size:           8
        .value_kind:     hidden_global_offset_z
      - .offset:         264
        .size:           2
        .value_kind:     hidden_grid_dims
      - .offset:         288
        .size:           8
        .value_kind:     hidden_multigrid_sync_arg
      - .offset:         320
        .size:           4
        .value_kind:     hidden_dynamic_lds_size
    .group_segment_fixed_size: 0
    .kernarg_segment_align: 8
    .kernarg_segment_size: 456
    .language:       OpenCL C
    .language_version:
      - 2
      - 0
    .max_flat_workgroup_size: 512
    .name:           _Z6mk_fwd4Args
    .private_segment_fixed_size: 0
    .sgpr_count:     108
    .sgpr_spill_count: 9
    .symbol:         _Z6mk_fwd4Args.kd
    .uniform_work_group_size: 1
    .uses_dynamic_stack: false
    .vgpr_count:     256
    .vgpr_spill_count: 0
    .wavefront_size: 64
